# grid barrier flat release: all workgroups poll the TOP arrival counter directly (TOP >= (gen+1)*nx), TOPGEN/XGEN release atomics dropped; on top of early inv + pre-clean wbl2
# speedup vs baseline: 1.0127x; 1.0002x over previous
.Lnopre_0:
	v_cmp_ne_u32_e32 vcc, v3, v2
	s_and_saveexec_b64 s[6:7], vcc
	s_xor_b64 s[6:7], exec, s[6:7]
	s_cbranch_execz .LBB0_155
	s_waitcnt lgkmcnt(0)
	v_add_u32_e32 v4, 1, v1
	v_mul_lo_u32 v4, v4, v0
	v_mov_b32_e32 v0, 0x7000
	global_load_dword v0, v0, s[40:41] offset:1024 sc1
	s_add_u32 s12, s40, 0x7400
	s_addc_u32 s13, s41, 0
	s_waitcnt vmcnt(0)
	v_sub_u32_e32 v0, v0, v4
	v_cmp_gt_i32_e32 vcc, 0, v0
	s_and_saveexec_b64 s[8:9], vcc
	s_cbranch_execz .LBB0_154
	s_add_u32 s10, s40, 0x4200
	s_addc_u32 s11, s41, 0
	s_mov_b32 s44, 1
	s_mov_b64 s[18:19], 0
	v_mov_b32_e32 v0, 0
	s_branch .LBB0_145

.LBB0_147:
	global_load_dword v2, v0, s[12:13] sc1
	s_add_i32 s44, s44, 1
	s_mov_b64 s[30:31], -1
	s_waitcnt vmcnt(0)
	v_sub_u32_e32 v2, v2, v4
	v_cmp_le_i32_e32 vcc, 0, v2
	s_orn2_b64 s[24:25], vcc, exec
	s_branch .LBB0_144

.LBB0_158:
	s_or_b64 exec, exec, s[8:9]
	v_cvt_f32_u32_e32 v3, v0
	s_waitcnt vmcnt(0)
	v_readfirstlane_b32 s6, v2
	s_add_u32 s8, s40, 0x7500
	s_addc_u32 s9, s41, 0
	v_rcp_iflag_f32_e32 v3, v3
	v_add_u32_e32 v1, s6, v1
	v_add_u32_e32 v4, 1, v1
	s_mov_b64 s[10:11], 0
	v_mul_f32_e32 v2, 0x4f7ffffe, v3
	v_cvt_u32_f32_e32 v2, v2
	v_sub_u32_e32 v3, 0, v0
	v_mul_lo_u32 v3, v3, v2
	v_mul_hi_u32 v3, v2, v3
	v_add_u32_e32 v2, v2, v3
	v_mul_hi_u32 v2, v1, v2
	v_mul_lo_u32 v3, v2, v0
	v_sub_u32_e32 v1, v1, v3
	v_add_u32_e32 v5, 1, v2
	v_cmp_ge_u32_e32 vcc, v1, v0
	v_sub_u32_e32 v3, v1, v0
	s_nop 0
	v_cndmask_b32_e32 v2, v2, v5, vcc
	v_cndmask_b32_e32 v1, v1, v3, vcc
	v_add_u32_e32 v3, 1, v2
	v_cmp_ge_u32_e32 vcc, v1, v0
	s_nop 1
	v_cndmask_b32_e32 v2, v2, v3, vcc
	v_mul_lo_u32 v1, v0, v2
	v_add_u32_e32 v0, v1, v0
	v_cmp_ne_u32_e32 vcc, v4, v0
	v_mov_b32_e32 v5, v0
	v_mov_b64_e32 v[0:1], s[8:9]
	s_and_saveexec_b64 s[6:7], vcc
	s_cbranch_execz .LBB0_170
	v_mov_b32_e32 v0, 0
	global_load_dword v1, v0, s[8:9] offset:-256 sc1
	s_mov_b64 s[18:19], 0
	s_waitcnt vmcnt(0)
	v_sub_u32_e32 v1, v1, v5
	v_cmp_gt_i32_e32 vcc, 0, v1
	s_and_saveexec_b64 s[12:13], vcc
	s_cbranch_execz .LBB0_169
	s_add_u32 s10, s40, 0x4200
	s_addc_u32 s11, s41, 0
	s_mov_b32 s44, 1
	s_branch .LBB0_162

.LBB0_164:
	global_load_dword v1, v0, s[8:9] offset:-256 sc1
	s_add_i32 s44, s44, 1
	s_mov_b64 s[24:25], -1
	s_waitcnt vmcnt(0)
	v_sub_u32_e32 v1, v1, v5
	v_cmp_le_i32_e32 vcc, 0, v1
	s_orn2_b64 s[36:37], vcc, exec
	s_branch .LBB0_161

.LBB0_172:
	s_or_b64 exec, exec, s[6:7]
	s_mov_b64 s[6:7], exec
	v_mbcnt_lo_u32_b32 v0, s6, 0
	v_mbcnt_hi_u32_b32 v0, s7, v0
	v_cmp_eq_u32_e32 vcc, 0, v0
	s_and_saveexec_b64 s[8:9], vcc
	s_cbranch_execz .LBB0_174
	s_bcnt1_i32_b64 s6, s[6:7]
	v_mov_b32_e32 v0, 0x2000
	v_mov_b32_e32 v1, s6
.LBB0_174:
	s_or_b64 exec, exec, s[8:9]
	s_waitcnt vmcnt(0)

.Lnopre_1:
	v_cmp_ne_u32_e32 vcc, v3, v2
	s_and_saveexec_b64 s[6:7], vcc
	s_xor_b64 s[6:7], exec, s[6:7]
	s_cbranch_execz .LBB0_223
	s_waitcnt lgkmcnt(0)
	v_add_u32_e32 v4, 1, v1
	v_mul_lo_u32 v4, v4, v0
	v_mov_b32_e32 v0, 0x7000
	global_load_dword v0, v0, s[40:41] offset:1024 sc1
	s_add_u32 s12, s40, 0x7400
	s_addc_u32 s13, s41, 0
	s_waitcnt vmcnt(0)
	v_sub_u32_e32 v0, v0, v4
	v_cmp_gt_i32_e32 vcc, 0, v0
	s_and_saveexec_b64 s[8:9], vcc
	s_cbranch_execz .LBB0_222
	s_add_u32 s10, s40, 0x4200
	s_addc_u32 s11, s41, 0
	s_mov_b32 s48, 1
	s_mov_b64 s[24:25], 0
	v_mov_b32_e32 v0, 0
	s_branch .LBB0_213

.LBB0_215:
	global_load_dword v2, v0, s[12:13] sc1
	s_add_i32 s48, s48, 1
	s_mov_b64 s[44:45], -1
	s_waitcnt vmcnt(0)
	v_sub_u32_e32 v2, v2, v4
	v_cmp_le_i32_e32 vcc, 0, v2
	s_orn2_b64 s[36:37], vcc, exec
	s_branch .LBB0_212

.LBB0_226:
	s_or_b64 exec, exec, s[8:9]
	v_cvt_f32_u32_e32 v3, v0
	s_waitcnt vmcnt(0)
	v_readfirstlane_b32 s6, v2
	s_add_u32 s8, s40, 0x7500
	s_addc_u32 s9, s41, 0
	v_rcp_iflag_f32_e32 v3, v3
	v_add_u32_e32 v1, s6, v1
	v_add_u32_e32 v4, 1, v1
	s_mov_b64 s[10:11], 0
	v_mul_f32_e32 v2, 0x4f7ffffe, v3
	v_cvt_u32_f32_e32 v2, v2
	v_sub_u32_e32 v3, 0, v0
	v_mul_lo_u32 v3, v3, v2
	v_mul_hi_u32 v3, v2, v3
	v_add_u32_e32 v2, v2, v3
	v_mul_hi_u32 v2, v1, v2
	v_mul_lo_u32 v3, v2, v0
	v_sub_u32_e32 v1, v1, v3
	v_add_u32_e32 v5, 1, v2
	v_cmp_ge_u32_e32 vcc, v1, v0
	v_sub_u32_e32 v3, v1, v0
	s_nop 0
	v_cndmask_b32_e32 v2, v2, v5, vcc
	v_cndmask_b32_e32 v1, v1, v3, vcc
	v_add_u32_e32 v3, 1, v2
	v_cmp_ge_u32_e32 vcc, v1, v0
	s_nop 1
	v_cndmask_b32_e32 v2, v2, v3, vcc
	v_mul_lo_u32 v1, v0, v2
	v_add_u32_e32 v0, v1, v0
	v_cmp_ne_u32_e32 vcc, v4, v0
	v_mov_b32_e32 v5, v0
	v_mov_b64_e32 v[0:1], s[8:9]
	s_and_saveexec_b64 s[6:7], vcc
	s_cbranch_execz .LBB0_238
	v_mov_b32_e32 v0, 0
	global_load_dword v1, v0, s[8:9] offset:-256 sc1
	s_mov_b64 s[24:25], 0
	s_waitcnt vmcnt(0)
	v_sub_u32_e32 v1, v1, v5
	v_cmp_gt_i32_e32 vcc, 0, v1
	s_and_saveexec_b64 s[12:13], vcc
	s_cbranch_execz .LBB0_237
	s_add_u32 s10, s40, 0x4200
	s_addc_u32 s11, s41, 0
	s_mov_b32 s48, 1
	s_branch .LBB0_230

.LBB0_232:
	global_load_dword v1, v0, s[8:9] offset:-256 sc1
	s_add_i32 s48, s48, 1
	s_mov_b64 s[36:37], -1
	s_waitcnt vmcnt(0)
	v_sub_u32_e32 v1, v1, v5
	v_cmp_le_i32_e32 vcc, 0, v1
	s_orn2_b64 s[46:47], vcc, exec
	s_branch .LBB0_229

.LBB0_240:
	s_or_b64 exec, exec, s[6:7]
	s_mov_b64 s[6:7], exec
	v_mbcnt_lo_u32_b32 v0, s6, 0
	v_mbcnt_hi_u32_b32 v0, s7, v0
	v_cmp_eq_u32_e32 vcc, 0, v0
	s_and_saveexec_b64 s[8:9], vcc
	s_cbranch_execz .LBB0_242
	s_bcnt1_i32_b64 s6, s[6:7]
	v_mov_b32_e32 v0, 0x2000
	v_mov_b32_e32 v1, s6
.LBB0_242:
	s_or_b64 exec, exec, s[8:9]
	s_waitcnt vmcnt(0)

.Lnopre_2:
	v_cmp_ne_u32_e32 vcc, v3, v2
	s_and_saveexec_b64 s[6:7], vcc
	s_xor_b64 s[6:7], exec, s[6:7]
	s_cbranch_execz .LBB0_303
	s_waitcnt lgkmcnt(0)
	v_add_u32_e32 v4, 1, v1
	v_mul_lo_u32 v4, v4, v0
	v_mov_b32_e32 v0, 0x7000
	global_load_dword v0, v0, s[40:41] offset:1024 sc1
	s_add_u32 s30, s40, 0x7400
	s_addc_u32 s31, s41, 0
	s_waitcnt vmcnt(0)
	v_sub_u32_e32 v0, v0, v4
	v_cmp_gt_i32_e32 vcc, 0, v0
	s_and_saveexec_b64 s[8:9], vcc
	s_cbranch_execz .LBB0_302
	s_add_u32 s10, s40, 0x4200
	s_addc_u32 s11, s41, 0
	s_mov_b32 s54, 1
	s_mov_b64 s[36:37], 0
	v_mov_b32_e32 v0, 0
	s_branch .LBB0_293

.LBB0_295:
	global_load_dword v2, v0, s[30:31] sc1
	s_add_i32 s54, s54, 1
	s_mov_b64 s[48:49], -1
	s_waitcnt vmcnt(0)
	v_sub_u32_e32 v2, v2, v4
	v_cmp_le_i32_e32 vcc, 0, v2
	s_orn2_b64 s[46:47], vcc, exec
	s_branch .LBB0_292

.LBB0_306:
	s_or_b64 exec, exec, s[8:9]
	v_cvt_f32_u32_e32 v3, v0
	s_waitcnt vmcnt(0)
	v_readfirstlane_b32 s6, v2
	s_add_u32 s8, s40, 0x7500
	s_addc_u32 s9, s41, 0
	v_rcp_iflag_f32_e32 v3, v3
	v_add_u32_e32 v1, s6, v1
	v_add_u32_e32 v4, 1, v1
	s_mov_b64 s[10:11], 0
	v_mul_f32_e32 v2, 0x4f7ffffe, v3
	v_cvt_u32_f32_e32 v2, v2
	v_sub_u32_e32 v3, 0, v0
	v_mul_lo_u32 v3, v3, v2
	v_mul_hi_u32 v3, v2, v3
	v_add_u32_e32 v2, v2, v3
	v_mul_hi_u32 v2, v1, v2
	v_mul_lo_u32 v3, v2, v0
	v_sub_u32_e32 v1, v1, v3
	v_add_u32_e32 v5, 1, v2
	v_cmp_ge_u32_e32 vcc, v1, v0
	v_sub_u32_e32 v3, v1, v0
	s_nop 0
	v_cndmask_b32_e32 v2, v2, v5, vcc
	v_cndmask_b32_e32 v1, v1, v3, vcc
	v_add_u32_e32 v3, 1, v2
	v_cmp_ge_u32_e32 vcc, v1, v0
	s_nop 1
	v_cndmask_b32_e32 v2, v2, v3, vcc
	v_mul_lo_u32 v1, v0, v2
	v_add_u32_e32 v0, v1, v0
	v_cmp_ne_u32_e32 vcc, v4, v0
	v_mov_b32_e32 v5, v0
	v_mov_b64_e32 v[0:1], s[8:9]
	s_and_saveexec_b64 s[6:7], vcc
	s_cbranch_execz .LBB0_318
	v_mov_b32_e32 v0, 0
	global_load_dword v1, v0, s[8:9] offset:-256 sc1
	s_mov_b64 s[36:37], 0
	s_waitcnt vmcnt(0)
	v_sub_u32_e32 v1, v1, v5
	v_cmp_gt_i32_e32 vcc, 0, v1
	s_and_saveexec_b64 s[30:31], vcc
	s_cbranch_execz .LBB0_317
	s_add_u32 s10, s40, 0x4200
	s_addc_u32 s11, s41, 0
	s_mov_b32 s54, 1
	s_branch .LBB0_310

.LBB0_312:
	global_load_dword v1, v0, s[8:9] offset:-256 sc1
	s_add_i32 s54, s54, 1
	s_mov_b64 s[46:47], -1
	s_waitcnt vmcnt(0)
	v_sub_u32_e32 v1, v1, v5
	v_cmp_le_i32_e32 vcc, 0, v1
	s_orn2_b64 s[52:53], vcc, exec
	s_branch .LBB0_309

.LBB0_320:
	s_or_b64 exec, exec, s[6:7]
	s_mov_b64 s[6:7], exec
	v_mbcnt_lo_u32_b32 v0, s6, 0
	v_mbcnt_hi_u32_b32 v0, s7, v0
	v_cmp_eq_u32_e32 vcc, 0, v0
	s_and_saveexec_b64 s[8:9], vcc
	s_cbranch_execz .LBB0_322
	s_bcnt1_i32_b64 s6, s[6:7]
	v_mov_b32_e32 v0, 0x2000
	v_mov_b32_e32 v1, s6
.LBB0_322:
	s_or_b64 exec, exec, s[8:9]
	s_waitcnt vmcnt(0)

.Lnopre_3:
	v_cmp_ne_u32_e32 vcc, v3, v2
	s_and_saveexec_b64 s[6:7], vcc
	s_xor_b64 s[6:7], exec, s[6:7]
	s_cbranch_execz .LBB0_358
	s_waitcnt lgkmcnt(0)
	v_add_u32_e32 v4, 1, v1
	v_mul_lo_u32 v4, v4, v0
	v_mov_b32_e32 v0, 0x7000
	global_load_dword v0, v0, s[40:41] offset:1024 sc1
	s_add_u32 s16, s40, 0x7400
	s_addc_u32 s17, s41, 0
	s_waitcnt vmcnt(0)
	v_sub_u32_e32 v0, v0, v4
	v_cmp_gt_i32_e32 vcc, 0, v0
	s_and_saveexec_b64 s[8:9], vcc
	s_cbranch_execz .LBB0_357
	s_add_u32 s10, s40, 0x4200
	s_addc_u32 s11, s41, 0
	s_mov_b32 s54, 1
	s_mov_b64 s[36:37], 0
	v_mov_b32_e32 v0, 0
	s_branch .LBB0_348

.LBB0_350:
	global_load_dword v2, v0, s[16:17] sc1
	s_add_i32 s54, s54, 1
	s_mov_b64 s[48:49], -1
	s_waitcnt vmcnt(0)
	v_sub_u32_e32 v2, v2, v4
	v_cmp_le_i32_e32 vcc, 0, v2
	s_orn2_b64 s[46:47], vcc, exec
	s_branch .LBB0_347

.LBB0_361:
	s_or_b64 exec, exec, s[8:9]
	v_cvt_f32_u32_e32 v3, v0
	s_waitcnt vmcnt(0)
	v_readfirstlane_b32 s6, v2
	s_add_u32 s8, s40, 0x7500
	s_addc_u32 s9, s41, 0
	v_rcp_iflag_f32_e32 v3, v3
	v_add_u32_e32 v1, s6, v1
	v_add_u32_e32 v4, 1, v1
	s_mov_b64 s[10:11], 0
	v_mul_f32_e32 v2, 0x4f7ffffe, v3
	v_cvt_u32_f32_e32 v2, v2
	v_sub_u32_e32 v3, 0, v0
	v_mul_lo_u32 v3, v3, v2
	v_mul_hi_u32 v3, v2, v3
	v_add_u32_e32 v2, v2, v3
	v_mul_hi_u32 v2, v1, v2
	v_mul_lo_u32 v3, v2, v0
	v_sub_u32_e32 v1, v1, v3
	v_add_u32_e32 v5, 1, v2
	v_cmp_ge_u32_e32 vcc, v1, v0
	v_sub_u32_e32 v3, v1, v0
	s_nop 0
	v_cndmask_b32_e32 v2, v2, v5, vcc
	v_cndmask_b32_e32 v1, v1, v3, vcc
	v_add_u32_e32 v3, 1, v2
	v_cmp_ge_u32_e32 vcc, v1, v0
	s_nop 1
	v_cndmask_b32_e32 v2, v2, v3, vcc
	v_mul_lo_u32 v1, v0, v2
	v_add_u32_e32 v0, v1, v0
	v_cmp_ne_u32_e32 vcc, v4, v0
	v_mov_b32_e32 v5, v0
	v_mov_b64_e32 v[0:1], s[8:9]
	s_and_saveexec_b64 s[6:7], vcc
	s_cbranch_execz .LBB0_373
	v_mov_b32_e32 v0, 0
	global_load_dword v1, v0, s[8:9] offset:-256 sc1
	s_mov_b64 s[36:37], 0
	s_waitcnt vmcnt(0)
	v_sub_u32_e32 v1, v1, v5
	v_cmp_gt_i32_e32 vcc, 0, v1
	s_and_saveexec_b64 s[16:17], vcc
	s_cbranch_execz .LBB0_372
	s_add_u32 s10, s40, 0x4200
	s_addc_u32 s11, s41, 0
	s_mov_b32 s54, 1
	s_branch .LBB0_365

.LBB0_375:
	s_or_b64 exec, exec, s[6:7]
	s_mov_b64 s[6:7], exec
	v_mbcnt_lo_u32_b32 v0, s6, 0
	v_mbcnt_hi_u32_b32 v0, s7, v0
	v_cmp_eq_u32_e32 vcc, 0, v0
	s_and_saveexec_b64 s[8:9], vcc
	s_cbranch_execz .LBB0_377
	s_bcnt1_i32_b64 s6, s[6:7]
	v_mov_b32_e32 v0, 0x2000
	v_mov_b32_e32 v1, s6
.LBB0_377:
	s_or_b64 exec, exec, s[8:9]
	s_waitcnt vmcnt(0)

.LBB0_443:
	s_or_b64 exec, exec, s[6:7]
	s_mov_b64 s[6:7], exec
	v_mbcnt_lo_u32_b32 v0, s6, 0
	v_mbcnt_hi_u32_b32 v0, s7, v0
	v_cmp_eq_u32_e32 vcc, 0, v0
	s_and_saveexec_b64 s[8:9], vcc
	s_cbranch_execz .LBB0_445
	s_bcnt1_i32_b64 s6, s[6:7]
	v_mov_b32_e32 v0, 0x2000
	v_mov_b32_e32 v1, s6
.LBB0_445:
	s_or_b64 exec, exec, s[8:9]
	s_waitcnt vmcnt(0)

.Lnopre_5:
	v_cmp_ne_u32_e32 vcc, v3, v2
	s_and_saveexec_b64 s[6:7], vcc
	s_xor_b64 s[6:7], exec, s[6:7]
	s_cbranch_execz .LBB0_495
	s_waitcnt lgkmcnt(0)
	v_add_u32_e32 v4, 1, v1
	v_mul_lo_u32 v4, v4, v0
	v_mov_b32_e32 v0, 0x7000
	global_load_dword v0, v0, s[40:41] offset:1024 sc1
	s_add_u32 s44, s40, 0x7400
	s_addc_u32 s45, s41, 0
	s_waitcnt vmcnt(0)
	v_sub_u32_e32 v0, v0, v4
	v_cmp_gt_i32_e32 vcc, 0, v0
	s_and_saveexec_b64 s[16:17], vcc
	s_cbranch_execz .LBB0_494
	s_add_u32 s36, s40, 0x4200
	s_addc_u32 s37, s41, 0
	s_mov_b32 s58, 1
	s_mov_b64 s[46:47], 0
	v_mov_b32_e32 v0, 0
	s_branch .LBB0_485

.LBB0_487:
	global_load_dword v2, v0, s[44:45] sc1
	s_add_i32 s58, s58, 1
	s_mov_b64 s[54:55], -1
	s_waitcnt vmcnt(0)
	v_sub_u32_e32 v2, v2, v4
	v_cmp_le_i32_e32 vcc, 0, v2
	s_orn2_b64 s[52:53], vcc, exec
	s_branch .LBB0_484

.LBB0_498:
	s_or_b64 exec, exec, s[16:17]
	v_cvt_f32_u32_e32 v3, v0
	s_waitcnt vmcnt(0)
	v_readfirstlane_b32 s6, v2
	s_add_u32 s16, s40, 0x7500
	s_addc_u32 s17, s41, 0
	v_rcp_iflag_f32_e32 v3, v3
	v_add_u32_e32 v1, s6, v1
	v_add_u32_e32 v4, 1, v1
	s_mov_b64 s[36:37], 0
	v_mul_f32_e32 v2, 0x4f7ffffe, v3
	v_cvt_u32_f32_e32 v2, v2
	v_sub_u32_e32 v3, 0, v0
	v_mul_lo_u32 v3, v3, v2
	v_mul_hi_u32 v3, v2, v3
	v_add_u32_e32 v2, v2, v3
	v_mul_hi_u32 v2, v1, v2
	v_mul_lo_u32 v3, v2, v0
	v_sub_u32_e32 v1, v1, v3
	v_add_u32_e32 v5, 1, v2
	v_cmp_ge_u32_e32 vcc, v1, v0
	v_sub_u32_e32 v3, v1, v0
	s_nop 0
	v_cndmask_b32_e32 v2, v2, v5, vcc
	v_cndmask_b32_e32 v1, v1, v3, vcc
	v_add_u32_e32 v3, 1, v2
	v_cmp_ge_u32_e32 vcc, v1, v0
	s_nop 1
	v_cndmask_b32_e32 v2, v2, v3, vcc
	v_mul_lo_u32 v1, v0, v2
	v_add_u32_e32 v0, v1, v0
	v_cmp_ne_u32_e32 vcc, v4, v0
	v_mov_b32_e32 v5, v0
	v_mov_b64_e32 v[0:1], s[16:17]
	s_and_saveexec_b64 s[6:7], vcc
	s_cbranch_execz .LBB0_510
	v_mov_b32_e32 v0, 0
	global_load_dword v1, v0, s[16:17] offset:-256 sc1
	s_mov_b64 s[46:47], 0
	s_waitcnt vmcnt(0)
	v_sub_u32_e32 v1, v1, v5
	v_cmp_gt_i32_e32 vcc, 0, v1
	s_and_saveexec_b64 s[44:45], vcc
	s_cbranch_execz .LBB0_509
	s_add_u32 s36, s40, 0x4200
	s_addc_u32 s37, s41, 0
	s_mov_b32 s58, 1
	s_branch .LBB0_502

.LBB0_504:
	global_load_dword v1, v0, s[16:17] offset:-256 sc1
	s_add_i32 s58, s58, 1
	s_mov_b64 s[52:53], -1
	s_waitcnt vmcnt(0)
	v_sub_u32_e32 v1, v1, v5
	v_cmp_le_i32_e32 vcc, 0, v1
	s_orn2_b64 s[56:57], vcc, exec
	s_branch .LBB0_501

.LBB0_512:
	s_or_b64 exec, exec, s[6:7]
	s_mov_b64 s[6:7], exec
	v_mbcnt_lo_u32_b32 v0, s6, 0
	v_mbcnt_hi_u32_b32 v0, s7, v0
	v_cmp_eq_u32_e32 vcc, 0, v0
	s_and_saveexec_b64 s[16:17], vcc
	s_cbranch_execz .LBB0_514
	s_bcnt1_i32_b64 s6, s[6:7]
	v_mov_b32_e32 v0, 0x2000
	v_mov_b32_e32 v1, s6
.LBB0_514:
	s_or_b64 exec, exec, s[16:17]
	s_waitcnt vmcnt(0)

.LBB0_581:
	s_or_b64 exec, exec, s[6:7]
	s_mov_b64 s[6:7], exec
	v_mbcnt_lo_u32_b32 v0, s6, 0
	v_mbcnt_hi_u32_b32 v0, s7, v0
	v_cmp_eq_u32_e32 vcc, 0, v0
	s_and_saveexec_b64 s[8:9], vcc
	s_cbranch_execz .LBB0_583
	s_bcnt1_i32_b64 s6, s[6:7]
	v_mov_b32_e32 v0, 0x2000
	v_mov_b32_e32 v1, s6
.LBB0_583:
	s_or_b64 exec, exec, s[8:9]
	s_waitcnt vmcnt(0)

.Lnopre_7:
	v_cmp_ne_u32_e32 vcc, v3, v2
	s_and_saveexec_b64 s[8:9], vcc
	s_xor_b64 s[8:9], exec, s[8:9]
	s_cbranch_execz .LBB0_640
	s_waitcnt lgkmcnt(0)
	v_add_u32_e32 v4, 1, v1
	v_mul_lo_u32 v4, v4, v0
	v_mov_b32_e32 v0, 0x7000
	global_load_dword v0, v0, s[40:41] offset:1024 sc1
	s_add_u32 s16, s40, 0x7400
	s_addc_u32 s17, s41, 0
	s_waitcnt vmcnt(0)
	v_sub_u32_e32 v0, v0, v4
	v_cmp_gt_i32_e32 vcc, 0, v0
	s_and_saveexec_b64 s[10:11], vcc
	s_cbranch_execz .LBB0_639
	s_add_u32 s12, s40, 0x4200
	s_addc_u32 s13, s41, 0
	s_mov_b32 s54, 1
	s_mov_b64 s[36:37], 0
	v_mov_b32_e32 v0, 0
	s_branch .LBB0_630

.LBB0_643:
	s_or_b64 exec, exec, s[10:11]
	v_cvt_f32_u32_e32 v3, v0
	s_waitcnt vmcnt(0)
	v_readfirstlane_b32 s8, v2
	s_add_u32 s10, s40, 0x7500
	s_addc_u32 s11, s41, 0
	v_rcp_iflag_f32_e32 v3, v3
	v_add_u32_e32 v1, s8, v1
	v_add_u32_e32 v4, 1, v1
	s_mov_b64 s[12:13], 0
	v_mul_f32_e32 v2, 0x4f7ffffe, v3
	v_cvt_u32_f32_e32 v2, v2
	v_sub_u32_e32 v3, 0, v0
	v_mul_lo_u32 v3, v3, v2
	v_mul_hi_u32 v3, v2, v3
	v_add_u32_e32 v2, v2, v3
	v_mul_hi_u32 v2, v1, v2
	v_mul_lo_u32 v3, v2, v0
	v_sub_u32_e32 v1, v1, v3
	v_add_u32_e32 v5, 1, v2
	v_cmp_ge_u32_e32 vcc, v1, v0
	v_sub_u32_e32 v3, v1, v0
	s_nop 0
	v_cndmask_b32_e32 v2, v2, v5, vcc
	v_cndmask_b32_e32 v1, v1, v3, vcc
	v_add_u32_e32 v3, 1, v2
	v_cmp_ge_u32_e32 vcc, v1, v0
	s_nop 1
	v_cndmask_b32_e32 v2, v2, v3, vcc
	v_mul_lo_u32 v1, v0, v2
	v_add_u32_e32 v0, v1, v0
	v_cmp_ne_u32_e32 vcc, v4, v0
	v_mov_b32_e32 v5, v0
	v_mov_b64_e32 v[0:1], s[10:11]
	s_and_saveexec_b64 s[8:9], vcc
	s_cbranch_execz .LBB0_655
	v_mov_b32_e32 v0, 0
	global_load_dword v1, v0, s[10:11] offset:-256 sc1
	s_mov_b64 s[36:37], 0
	s_waitcnt vmcnt(0)
	v_sub_u32_e32 v1, v1, v5
	v_cmp_gt_i32_e32 vcc, 0, v1
	s_and_saveexec_b64 s[16:17], vcc
	s_cbranch_execz .LBB0_654
	s_add_u32 s12, s40, 0x4200
	s_addc_u32 s13, s41, 0
	s_mov_b32 s54, 1
	s_branch .LBB0_647

.LBB0_649:
	global_load_dword v1, v0, s[10:11] offset:-256 sc1
	s_add_i32 s54, s54, 1
	s_mov_b64 s[46:47], -1
	s_waitcnt vmcnt(0)
	v_sub_u32_e32 v1, v1, v5
	v_cmp_le_i32_e32 vcc, 0, v1
	s_orn2_b64 s[52:53], vcc, exec
	s_branch .LBB0_646

.LBB0_657:
	s_or_b64 exec, exec, s[8:9]
	s_mov_b64 s[8:9], exec
	v_mbcnt_lo_u32_b32 v0, s8, 0
	v_mbcnt_hi_u32_b32 v0, s9, v0
	v_cmp_eq_u32_e32 vcc, 0, v0
	s_and_saveexec_b64 s[10:11], vcc
	s_cbranch_execz .LBB0_659
	s_bcnt1_i32_b64 s8, s[8:9]
	v_mov_b32_e32 v0, 0x2000
	v_mov_b32_e32 v1, s8
.LBB0_659:
	s_or_b64 exec, exec, s[10:11]
	s_waitcnt vmcnt(0)

.Lnopre_8:
	v_cmp_ne_u32_e32 vcc, v3, v2
	s_and_saveexec_b64 s[10:11], vcc
	s_xor_b64 s[10:11], exec, s[10:11]
	s_cbranch_execz .LBB0_695
	s_waitcnt lgkmcnt(0)
	v_add_u32_e32 v4, 1, v1
	v_mul_lo_u32 v4, v4, v0
	v_mov_b32_e32 v0, 0x7000
	global_load_dword v0, v0, s[40:41] offset:1024 sc1
	s_add_u32 s30, s40, 0x7400
	s_addc_u32 s31, s41, 0
	s_waitcnt vmcnt(0)
	v_sub_u32_e32 v0, v0, v4
	v_cmp_gt_i32_e32 vcc, 0, v0
	s_and_saveexec_b64 s[12:13], vcc
	s_cbranch_execz .LBB0_694
	s_add_u32 s16, s40, 0x4200
	s_addc_u32 s17, s41, 0
	s_mov_b32 s54, 1
	s_mov_b64 s[36:37], 0
	v_mov_b32_e32 v0, 0
	s_branch .LBB0_685

.LBB0_698:
	s_or_b64 exec, exec, s[12:13]
	v_cvt_f32_u32_e32 v3, v0
	s_waitcnt vmcnt(0)
	v_readfirstlane_b32 s10, v2
	s_add_u32 s12, s40, 0x7500
	s_addc_u32 s13, s41, 0
	v_rcp_iflag_f32_e32 v3, v3
	v_add_u32_e32 v1, s10, v1
	v_add_u32_e32 v4, 1, v1
	s_mov_b64 s[16:17], 0
	v_mul_f32_e32 v2, 0x4f7ffffe, v3
	v_cvt_u32_f32_e32 v2, v2
	v_sub_u32_e32 v3, 0, v0
	v_mul_lo_u32 v3, v3, v2
	v_mul_hi_u32 v3, v2, v3
	v_add_u32_e32 v2, v2, v3
	v_mul_hi_u32 v2, v1, v2
	v_mul_lo_u32 v3, v2, v0
	v_sub_u32_e32 v1, v1, v3
	v_add_u32_e32 v5, 1, v2
	v_cmp_ge_u32_e32 vcc, v1, v0
	v_sub_u32_e32 v3, v1, v0
	s_nop 0
	v_cndmask_b32_e32 v2, v2, v5, vcc
	v_cndmask_b32_e32 v1, v1, v3, vcc
	v_add_u32_e32 v3, 1, v2
	v_cmp_ge_u32_e32 vcc, v1, v0
	s_nop 1
	v_cndmask_b32_e32 v2, v2, v3, vcc
	v_mul_lo_u32 v1, v0, v2
	v_add_u32_e32 v0, v1, v0
	v_cmp_ne_u32_e32 vcc, v4, v0
	v_mov_b32_e32 v5, v0
	v_mov_b64_e32 v[0:1], s[12:13]
	s_and_saveexec_b64 s[10:11], vcc
	s_cbranch_execz .LBB0_710
	v_mov_b32_e32 v0, 0
	global_load_dword v1, v0, s[12:13] offset:-256 sc1
	s_mov_b64 s[36:37], 0
	s_waitcnt vmcnt(0)
	v_sub_u32_e32 v1, v1, v5
	v_cmp_gt_i32_e32 vcc, 0, v1
	s_and_saveexec_b64 s[30:31], vcc
	s_cbranch_execz .LBB0_709
	s_add_u32 s16, s40, 0x4200
	s_addc_u32 s17, s41, 0
	s_mov_b32 s54, 1
	s_branch .LBB0_702

.LBB0_704:
	global_load_dword v1, v0, s[12:13] offset:-256 sc1
	s_add_i32 s54, s54, 1
	s_mov_b64 s[46:47], -1
	s_waitcnt vmcnt(0)
	v_sub_u32_e32 v1, v1, v5
	v_cmp_le_i32_e32 vcc, 0, v1
	s_orn2_b64 s[52:53], vcc, exec
	s_branch .LBB0_701

.LBB0_712:
	s_or_b64 exec, exec, s[10:11]
	s_mov_b64 s[10:11], exec
	v_mbcnt_lo_u32_b32 v0, s10, 0
	v_mbcnt_hi_u32_b32 v0, s11, v0
	v_cmp_eq_u32_e32 vcc, 0, v0
	s_and_saveexec_b64 s[12:13], vcc
	s_cbranch_execz .LBB0_714
	s_bcnt1_i32_b64 s10, s[10:11]
	v_mov_b32_e32 v0, 0x2000
	v_mov_b32_e32 v1, s10
.LBB0_714:
	s_or_b64 exec, exec, s[12:13]
	s_waitcnt vmcnt(0)

.Lnopre_9:
	v_cmp_ne_u32_e32 vcc, v3, v2
	s_and_saveexec_b64 s[12:13], vcc
	s_xor_b64 s[12:13], exec, s[12:13]
	s_cbranch_execz .LBB0_763
	s_waitcnt lgkmcnt(0)
	v_add_u32_e32 v4, 1, v1
	v_mul_lo_u32 v4, v4, v0
	v_mov_b32_e32 v0, 0x7000
	global_load_dword v0, v0, s[40:41] offset:1024 sc1
	s_add_u32 s30, s40, 0x7400
	s_addc_u32 s31, s41, 0
	s_waitcnt vmcnt(0)
	v_sub_u32_e32 v0, v0, v4
	v_cmp_gt_i32_e32 vcc, 0, v0
	s_and_saveexec_b64 s[16:17], vcc
	s_cbranch_execz .LBB0_762
	s_add_u32 s18, s40, 0x4200
	s_addc_u32 s19, s41, 0
	s_mov_b32 s54, 1
	s_mov_b64 s[36:37], 0
	v_mov_b32_e32 v0, 0
	s_branch .LBB0_753

.LBB0_766:
	s_or_b64 exec, exec, s[16:17]
	v_cvt_f32_u32_e32 v3, v0
	s_waitcnt vmcnt(0)
	v_readfirstlane_b32 s12, v2
	s_add_u32 s16, s40, 0x7500
	s_addc_u32 s17, s41, 0
	v_rcp_iflag_f32_e32 v3, v3
	v_add_u32_e32 v1, s12, v1
	v_add_u32_e32 v4, 1, v1
	s_mov_b64 s[18:19], 0
	v_mul_f32_e32 v2, 0x4f7ffffe, v3
	v_cvt_u32_f32_e32 v2, v2
	v_sub_u32_e32 v3, 0, v0
	v_mul_lo_u32 v3, v3, v2
	v_mul_hi_u32 v3, v2, v3
	v_add_u32_e32 v2, v2, v3
	v_mul_hi_u32 v2, v1, v2
	v_mul_lo_u32 v3, v2, v0
	v_sub_u32_e32 v1, v1, v3
	v_add_u32_e32 v5, 1, v2
	v_cmp_ge_u32_e32 vcc, v1, v0
	v_sub_u32_e32 v3, v1, v0
	s_nop 0
	v_cndmask_b32_e32 v2, v2, v5, vcc
	v_cndmask_b32_e32 v1, v1, v3, vcc
	v_add_u32_e32 v3, 1, v2
	v_cmp_ge_u32_e32 vcc, v1, v0
	s_nop 1
	v_cndmask_b32_e32 v2, v2, v3, vcc
	v_mul_lo_u32 v1, v0, v2
	v_add_u32_e32 v0, v1, v0
	v_cmp_ne_u32_e32 vcc, v4, v0
	v_mov_b32_e32 v5, v0
	v_mov_b64_e32 v[0:1], s[16:17]
	s_and_saveexec_b64 s[12:13], vcc
	s_cbranch_execz .LBB0_778
	v_mov_b32_e32 v0, 0
	global_load_dword v1, v0, s[16:17] offset:-256 sc1
	s_mov_b64 s[36:37], 0
	s_waitcnt vmcnt(0)
	v_sub_u32_e32 v1, v1, v5
	v_cmp_gt_i32_e32 vcc, 0, v1
	s_and_saveexec_b64 s[30:31], vcc
	s_cbranch_execz .LBB0_777
	s_add_u32 s18, s40, 0x4200
	s_addc_u32 s19, s41, 0
	s_mov_b32 s54, 1
	s_branch .LBB0_770

.LBB0_772:
	global_load_dword v1, v0, s[16:17] offset:-256 sc1
	s_add_i32 s54, s54, 1
	s_mov_b64 s[46:47], -1
	s_waitcnt vmcnt(0)
	v_sub_u32_e32 v1, v1, v5
	v_cmp_le_i32_e32 vcc, 0, v1
	s_orn2_b64 s[52:53], vcc, exec
	s_branch .LBB0_769

.LBB0_780:
	s_or_b64 exec, exec, s[12:13]
	s_mov_b64 s[12:13], exec
	v_mbcnt_lo_u32_b32 v0, s12, 0
	v_mbcnt_hi_u32_b32 v0, s13, v0
	v_cmp_eq_u32_e32 vcc, 0, v0
	s_and_saveexec_b64 s[16:17], vcc
	s_cbranch_execz .LBB0_782
	s_bcnt1_i32_b64 s12, s[12:13]
	v_mov_b32_e32 v0, 0x2000
	v_mov_b32_e32 v1, s12
.LBB0_782:
	s_or_b64 exec, exec, s[16:17]
	s_waitcnt vmcnt(0)

.LBB0_860:
	s_or_b64 exec, exec, s[12:13]
	s_mov_b64 s[12:13], exec
	v_mbcnt_lo_u32_b32 v0, s12, 0
	v_mbcnt_hi_u32_b32 v0, s13, v0
	v_cmp_eq_u32_e32 vcc, 0, v0
	s_and_saveexec_b64 s[16:17], vcc
	s_cbranch_execz .LBB0_862
	s_bcnt1_i32_b64 s12, s[12:13]
	v_mov_b32_e32 v0, 0x2000
	v_mov_b32_e32 v1, s12
.LBB0_862:
	s_or_b64 exec, exec, s[16:17]
	s_waitcnt vmcnt(0)

.LBB0_915:
	s_or_b64 exec, exec, s[12:13]
	s_mov_b64 s[12:13], exec
	v_mbcnt_lo_u32_b32 v0, s12, 0
	v_mbcnt_hi_u32_b32 v0, s13, v0
	v_cmp_eq_u32_e32 vcc, 0, v0
	s_and_saveexec_b64 s[16:17], vcc
	s_cbranch_execz .LBB0_917
	s_bcnt1_i32_b64 s12, s[12:13]
	v_mov_b32_e32 v0, 0x2000
	v_mov_b32_e32 v1, s12
.LBB0_917:
	s_or_b64 exec, exec, s[16:17]
	s_waitcnt vmcnt(0)

.Lnopre_12:
	v_cmp_ne_u32_e32 vcc, v3, v2
	s_and_saveexec_b64 s[12:13], vcc
	s_xor_b64 s[12:13], exec, s[12:13]
	s_cbranch_execz .LBB0_990
	s_waitcnt lgkmcnt(0)
	v_add_u32_e32 v4, 1, v1
	v_mul_lo_u32 v4, v4, v0
	v_mov_b32_e32 v0, 0x7000
	global_load_dword v0, v0, s[40:41] offset:1024 sc1
	s_add_u32 s36, s40, 0x7400
	s_addc_u32 s37, s41, 0
	s_waitcnt vmcnt(0)
	v_sub_u32_e32 v0, v0, v4
	v_cmp_gt_i32_e32 vcc, 0, v0
	s_and_saveexec_b64 s[16:17], vcc
	s_cbranch_execz .LBB0_989
	s_add_u32 s18, s40, 0x4200
	s_addc_u32 s19, s41, 0
	s_mov_b32 s56, 1
	s_mov_b64 s[44:45], 0
	v_mov_b32_e32 v0, 0
	s_branch .LBB0_980

.LBB0_982:
	global_load_dword v2, v0, s[36:37] sc1
	s_add_i32 s56, s56, 1
	s_mov_b64 s[52:53], -1
	s_waitcnt vmcnt(0)
	v_sub_u32_e32 v2, v2, v4
	v_cmp_le_i32_e32 vcc, 0, v2
	s_orn2_b64 s[48:49], vcc, exec
	s_branch .LBB0_979

.LBB0_993:
	s_or_b64 exec, exec, s[16:17]
	v_cvt_f32_u32_e32 v3, v0
	s_waitcnt vmcnt(0)
	v_readfirstlane_b32 s12, v2
	s_add_u32 s16, s40, 0x7500
	s_addc_u32 s17, s41, 0
	v_rcp_iflag_f32_e32 v3, v3
	v_add_u32_e32 v1, s12, v1
	v_add_u32_e32 v4, 1, v1
	s_mov_b64 s[18:19], 0
	v_mul_f32_e32 v2, 0x4f7ffffe, v3
	v_cvt_u32_f32_e32 v2, v2
	v_sub_u32_e32 v3, 0, v0
	v_mul_lo_u32 v3, v3, v2
	v_mul_hi_u32 v3, v2, v3
	v_add_u32_e32 v2, v2, v3
	v_mul_hi_u32 v2, v1, v2
	v_mul_lo_u32 v3, v2, v0
	v_sub_u32_e32 v1, v1, v3
	v_add_u32_e32 v5, 1, v2
	v_cmp_ge_u32_e32 vcc, v1, v0
	v_sub_u32_e32 v3, v1, v0
	s_nop 0
	v_cndmask_b32_e32 v2, v2, v5, vcc
	v_cndmask_b32_e32 v1, v1, v3, vcc
	v_add_u32_e32 v3, 1, v2
	v_cmp_ge_u32_e32 vcc, v1, v0
	s_nop 1
	v_cndmask_b32_e32 v2, v2, v3, vcc
	v_mul_lo_u32 v1, v0, v2
	v_add_u32_e32 v0, v1, v0
	v_cmp_ne_u32_e32 vcc, v4, v0
	v_mov_b32_e32 v5, v0
	v_mov_b64_e32 v[0:1], s[16:17]
	s_and_saveexec_b64 s[12:13], vcc
	s_cbranch_execz .LBB0_1005
	v_mov_b32_e32 v0, 0
	global_load_dword v1, v0, s[16:17] offset:-256 sc1
	s_mov_b64 s[44:45], 0
	s_waitcnt vmcnt(0)
	v_sub_u32_e32 v1, v1, v5
	v_cmp_gt_i32_e32 vcc, 0, v1
	s_and_saveexec_b64 s[36:37], vcc
	s_cbranch_execz .LBB0_1004
	s_add_u32 s18, s40, 0x4200
	s_addc_u32 s19, s41, 0
	s_mov_b32 s56, 1
	s_branch .LBB0_997

.LBB0_999:
	global_load_dword v1, v0, s[16:17] offset:-256 sc1
	s_add_i32 s56, s56, 1
	s_mov_b64 s[48:49], -1
	s_waitcnt vmcnt(0)
	v_sub_u32_e32 v1, v1, v5
	v_cmp_le_i32_e32 vcc, 0, v1
	s_orn2_b64 s[54:55], vcc, exec
	s_branch .LBB0_996

.LBB0_1007:
	s_or_b64 exec, exec, s[12:13]
	s_mov_b64 s[12:13], exec
	v_mbcnt_lo_u32_b32 v0, s12, 0
	v_mbcnt_hi_u32_b32 v0, s13, v0
	v_cmp_eq_u32_e32 vcc, 0, v0
	s_and_saveexec_b64 s[16:17], vcc
	s_cbranch_execz .LBB0_1009
	s_bcnt1_i32_b64 s12, s[12:13]
	v_mov_b32_e32 v0, 0x2000
	v_mov_b32_e32 v1, s12
.LBB0_1009:
	s_or_b64 exec, exec, s[16:17]
	s_waitcnt vmcnt(0)

.LBB0_1087:
	s_or_b64 exec, exec, s[12:13]
	s_mov_b64 s[12:13], exec
	v_mbcnt_lo_u32_b32 v0, s12, 0
	v_mbcnt_hi_u32_b32 v0, s13, v0
	v_cmp_eq_u32_e32 vcc, 0, v0
	s_and_saveexec_b64 s[16:17], vcc
	s_cbranch_execz .LBB0_1089
	s_bcnt1_i32_b64 s12, s[12:13]
	v_mov_b32_e32 v0, 0x2000
	v_mov_b32_e32 v1, s12
.LBB0_1089:
	s_or_b64 exec, exec, s[16:17]
	s_waitcnt vmcnt(0)

.LBB0_1142:
	s_or_b64 exec, exec, s[12:13]
	s_mov_b64 s[12:13], exec
	v_mbcnt_lo_u32_b32 v0, s12, 0
	v_mbcnt_hi_u32_b32 v0, s13, v0
	v_cmp_eq_u32_e32 vcc, 0, v0
	s_and_saveexec_b64 s[16:17], vcc
	s_cbranch_execz .LBB0_1144
	s_bcnt1_i32_b64 s12, s[12:13]
	v_mov_b32_e32 v0, 0x2000
	v_mov_b32_e32 v1, s12
.LBB0_1144:
	s_or_b64 exec, exec, s[16:17]
	s_waitcnt vmcnt(0)

.LBB0_1218:
	s_or_b64 exec, exec, s[12:13]
	s_mov_b64 s[12:13], exec
	v_mbcnt_lo_u32_b32 v0, s12, 0
	v_mbcnt_hi_u32_b32 v0, s13, v0
	v_cmp_eq_u32_e32 vcc, 0, v0
	s_and_saveexec_b64 s[16:17], vcc
	s_cbranch_execz .LBB0_1220
	s_bcnt1_i32_b64 s12, s[12:13]
	v_mov_b32_e32 v0, 0x2000
	v_mov_b32_e32 v1, s12
.LBB0_1220:
	s_or_b64 exec, exec, s[16:17]
	s_waitcnt vmcnt(0)

.Lnopre_16:
	v_cmp_ne_u32_e32 vcc, v3, v2
	s_and_saveexec_b64 s[12:13], vcc
	s_xor_b64 s[12:13], exec, s[12:13]
	s_cbranch_execz .LBB0_1274
	s_waitcnt lgkmcnt(0)
	v_add_u32_e32 v4, 1, v1
	v_mul_lo_u32 v4, v4, v0
	v_mov_b32_e32 v0, 0x7000
	global_load_dword v0, v0, s[40:41] offset:1024 sc1
	s_add_u32 s30, s40, 0x7400
	s_addc_u32 s31, s41, 0
	s_waitcnt vmcnt(0)
	v_sub_u32_e32 v0, v0, v4
	v_cmp_gt_i32_e32 vcc, 0, v0
	s_and_saveexec_b64 s[16:17], vcc
	s_cbranch_execz .LBB0_1273
	s_add_u32 s18, s40, 0x4200
	s_addc_u32 s19, s41, 0
	s_mov_b32 s52, 1
	s_mov_b64 s[36:37], 0
	v_mov_b32_e32 v0, 0
	s_branch .LBB0_1264

.LBB0_1266:
	global_load_dword v2, v0, s[30:31] sc1
	s_add_i32 s52, s52, 1
	s_mov_b64 s[48:49], -1
	s_waitcnt vmcnt(0)
	v_sub_u32_e32 v2, v2, v4
	v_cmp_le_i32_e32 vcc, 0, v2
	s_orn2_b64 s[46:47], vcc, exec
	s_branch .LBB0_1263

.LBB0_1277:
	s_or_b64 exec, exec, s[16:17]
	v_cvt_f32_u32_e32 v3, v0
	s_waitcnt vmcnt(0)
	v_readfirstlane_b32 s12, v2
	s_add_u32 s16, s40, 0x7500
	s_addc_u32 s17, s41, 0
	v_rcp_iflag_f32_e32 v3, v3
	v_add_u32_e32 v1, s12, v1
	v_add_u32_e32 v4, 1, v1
	s_mov_b64 s[18:19], 0
	v_mul_f32_e32 v2, 0x4f7ffffe, v3
	v_cvt_u32_f32_e32 v2, v2
	v_sub_u32_e32 v3, 0, v0
	v_mul_lo_u32 v3, v3, v2
	v_mul_hi_u32 v3, v2, v3
	v_add_u32_e32 v2, v2, v3
	v_mul_hi_u32 v2, v1, v2
	v_mul_lo_u32 v3, v2, v0
	v_sub_u32_e32 v1, v1, v3
	v_add_u32_e32 v5, 1, v2
	v_cmp_ge_u32_e32 vcc, v1, v0
	v_sub_u32_e32 v3, v1, v0
	s_nop 0
	v_cndmask_b32_e32 v2, v2, v5, vcc
	v_cndmask_b32_e32 v1, v1, v3, vcc
	v_add_u32_e32 v3, 1, v2
	v_cmp_ge_u32_e32 vcc, v1, v0
	s_nop 1
	v_cndmask_b32_e32 v2, v2, v3, vcc
	v_mul_lo_u32 v1, v0, v2
	v_add_u32_e32 v0, v1, v0
	v_cmp_ne_u32_e32 vcc, v4, v0
	v_mov_b32_e32 v5, v0
	v_mov_b64_e32 v[0:1], s[16:17]
	s_and_saveexec_b64 s[12:13], vcc
	s_cbranch_execz .LBB0_1289
	v_mov_b32_e32 v0, 0
	global_load_dword v1, v0, s[16:17] offset:-256 sc1
	s_mov_b64 s[36:37], 0
	s_waitcnt vmcnt(0)
	v_sub_u32_e32 v1, v1, v5
	v_cmp_gt_i32_e32 vcc, 0, v1
	s_and_saveexec_b64 s[30:31], vcc
	s_cbranch_execz .LBB0_1288
	s_add_u32 s18, s40, 0x4200
	s_addc_u32 s19, s41, 0
	s_mov_b32 s52, 1
	s_branch .LBB0_1281

.LBB0_1283:
	global_load_dword v1, v0, s[16:17] offset:-256 sc1
	s_add_i32 s52, s52, 1
	s_mov_b64 s[46:47], -1
	s_waitcnt vmcnt(0)
	v_sub_u32_e32 v1, v1, v5
	v_cmp_le_i32_e32 vcc, 0, v1
	s_orn2_b64 s[50:51], vcc, exec
	s_branch .LBB0_1280

.LBB0_1291:
	s_or_b64 exec, exec, s[12:13]
	s_mov_b64 s[12:13], exec
	v_mbcnt_lo_u32_b32 v0, s12, 0
	v_mbcnt_hi_u32_b32 v0, s13, v0
	v_cmp_eq_u32_e32 vcc, 0, v0
	s_and_saveexec_b64 s[16:17], vcc
	s_cbranch_execz .LBB0_1293
	s_bcnt1_i32_b64 s12, s[12:13]
	v_mov_b32_e32 v0, 0x2000
	v_mov_b32_e32 v1, s12
.LBB0_1293:
	s_or_b64 exec, exec, s[16:17]
	s_waitcnt vmcnt(0)

.LBB0_1367:
	s_or_b64 exec, exec, s[12:13]
	s_mov_b64 s[12:13], exec
	v_mbcnt_lo_u32_b32 v0, s12, 0
	v_mbcnt_hi_u32_b32 v0, s13, v0
	v_cmp_eq_u32_e32 vcc, 0, v0
	s_and_saveexec_b64 s[16:17], vcc
	s_cbranch_execz .LBB0_1369
	s_bcnt1_i32_b64 s12, s[12:13]
	v_mov_b32_e32 v0, 0x2000
	v_mov_b32_e32 v1, s12
.LBB0_1369:
	s_or_b64 exec, exec, s[16:17]
	s_waitcnt vmcnt(0)

.LBB0_1422:
	s_or_b64 exec, exec, s[12:13]
	s_mov_b64 s[12:13], exec
	v_mbcnt_lo_u32_b32 v0, s12, 0
	v_mbcnt_hi_u32_b32 v0, s13, v0
	v_cmp_eq_u32_e32 vcc, 0, v0
	s_and_saveexec_b64 s[16:17], vcc
	s_cbranch_execz .LBB0_1424
	s_bcnt1_i32_b64 s12, s[12:13]
	v_mov_b32_e32 v0, 0x2000
	v_mov_b32_e32 v1, s12
.LBB0_1424:
	s_or_b64 exec, exec, s[16:17]
	s_waitcnt vmcnt(0)

.Lnopre_19:
	v_cmp_ne_u32_e32 vcc, v3, v2
	s_and_saveexec_b64 s[10:11], vcc
	s_xor_b64 s[10:11], exec, s[10:11]
	s_cbranch_execz .LBB0_1473
	s_waitcnt lgkmcnt(0)
	v_add_u32_e32 v4, 1, v1
	v_mul_lo_u32 v4, v4, v0
	v_mov_b32_e32 v0, 0x7000
	global_load_dword v0, v0, s[40:41] offset:1024 sc1
	s_add_u32 s18, s40, 0x7400
	s_addc_u32 s19, s41, 0
	s_waitcnt vmcnt(0)
	v_sub_u32_e32 v0, v0, v4
	v_cmp_gt_i32_e32 vcc, 0, v0
	s_and_saveexec_b64 s[12:13], vcc
	s_cbranch_execz .LBB0_1472
	s_add_u32 s16, s40, 0x4200
	s_addc_u32 s17, s41, 0
	s_mov_b32 s50, 1
	s_mov_b64 s[30:31], 0
	v_mov_b32_e32 v0, 0
	s_branch .LBB0_1463

.LBB0_1465:
	global_load_dword v2, v0, s[18:19] sc1
	s_add_i32 s50, s50, 1
	s_mov_b64 s[46:47], -1
	s_waitcnt vmcnt(0)
	v_sub_u32_e32 v2, v2, v4
	v_cmp_le_i32_e32 vcc, 0, v2
	s_orn2_b64 s[44:45], vcc, exec
	s_branch .LBB0_1462

.LBB0_1476:
	s_or_b64 exec, exec, s[12:13]
	v_cvt_f32_u32_e32 v3, v0
	s_waitcnt vmcnt(0)
	v_readfirstlane_b32 s10, v2
	s_add_u32 s12, s40, 0x7500
	s_addc_u32 s13, s41, 0
	v_rcp_iflag_f32_e32 v3, v3
	v_add_u32_e32 v1, s10, v1
	v_add_u32_e32 v4, 1, v1
	s_mov_b64 s[16:17], 0
	v_mul_f32_e32 v2, 0x4f7ffffe, v3
	v_cvt_u32_f32_e32 v2, v2
	v_sub_u32_e32 v3, 0, v0
	v_mul_lo_u32 v3, v3, v2
	v_mul_hi_u32 v3, v2, v3
	v_add_u32_e32 v2, v2, v3
	v_mul_hi_u32 v2, v1, v2
	v_mul_lo_u32 v3, v2, v0
	v_sub_u32_e32 v1, v1, v3
	v_add_u32_e32 v5, 1, v2
	v_cmp_ge_u32_e32 vcc, v1, v0
	v_sub_u32_e32 v3, v1, v0
	s_nop 0
	v_cndmask_b32_e32 v2, v2, v5, vcc
	v_cndmask_b32_e32 v1, v1, v3, vcc
	v_add_u32_e32 v3, 1, v2
	v_cmp_ge_u32_e32 vcc, v1, v0
	s_nop 1
	v_cndmask_b32_e32 v2, v2, v3, vcc
	v_mul_lo_u32 v1, v0, v2
	v_add_u32_e32 v0, v1, v0
	v_cmp_ne_u32_e32 vcc, v4, v0
	v_mov_b32_e32 v5, v0
	v_mov_b64_e32 v[0:1], s[12:13]
	s_and_saveexec_b64 s[10:11], vcc
	s_cbranch_execz .LBB0_1488
	v_mov_b32_e32 v0, 0
	global_load_dword v1, v0, s[12:13] offset:-256 sc1
	s_mov_b64 s[30:31], 0
	s_waitcnt vmcnt(0)
	v_sub_u32_e32 v1, v1, v5
	v_cmp_gt_i32_e32 vcc, 0, v1
	s_and_saveexec_b64 s[18:19], vcc
	s_cbranch_execz .LBB0_1487
	s_add_u32 s16, s40, 0x4200
	s_addc_u32 s17, s41, 0
	s_mov_b32 s50, 1
	s_branch .LBB0_1480

.LBB0_1482:
	global_load_dword v1, v0, s[12:13] offset:-256 sc1
	s_add_i32 s50, s50, 1
	s_mov_b64 s[44:45], -1
	s_waitcnt vmcnt(0)
	v_sub_u32_e32 v1, v1, v5
	v_cmp_le_i32_e32 vcc, 0, v1
	s_orn2_b64 s[48:49], vcc, exec
	s_branch .LBB0_1479

.LBB0_1490:
	s_or_b64 exec, exec, s[10:11]
	s_mov_b64 s[10:11], exec
	v_mbcnt_lo_u32_b32 v0, s10, 0
	v_mbcnt_hi_u32_b32 v0, s11, v0
	v_cmp_eq_u32_e32 vcc, 0, v0
	s_and_saveexec_b64 s[12:13], vcc
	s_cbranch_execz .LBB0_1492
	s_bcnt1_i32_b64 s10, s[10:11]
	v_mov_b32_e32 v0, 0x2000
	v_mov_b32_e32 v1, s10
.LBB0_1492:
	s_or_b64 exec, exec, s[12:13]
	s_waitcnt vmcnt(0)

.Lnopre_20:
	v_cmp_ne_u32_e32 vcc, v3, v2
	s_and_saveexec_b64 s[6:7], vcc
	s_xor_b64 s[6:7], exec, s[6:7]
	s_cbranch_execz .LBB0_1553
	s_waitcnt lgkmcnt(0)
	v_add_u32_e32 v4, 1, v1
	v_mul_lo_u32 v4, v4, v0
	v_mov_b32_e32 v0, 0x7000
	global_load_dword v0, v0, s[40:41] offset:1024 sc1
	s_add_u32 s12, s40, 0x7400
	s_addc_u32 s13, s41, 0
	s_waitcnt vmcnt(0)
	v_sub_u32_e32 v0, v0, v4
	v_cmp_gt_i32_e32 vcc, 0, v0
	s_and_saveexec_b64 s[8:9], vcc
	s_cbranch_execz .LBB0_1552
	s_add_u32 s10, s40, 0x4200
	s_addc_u32 s11, s41, 0
	s_mov_b32 s24, 1
	s_mov_b64 s[14:15], 0
	v_mov_b32_e32 v0, 0
	s_branch .LBB0_1543

.LBB0_1545:
	global_load_dword v2, v0, s[12:13] sc1
	s_add_i32 s24, s24, 1
	s_mov_b64 s[20:21], -1
	s_waitcnt vmcnt(0)
	v_sub_u32_e32 v2, v2, v4
	v_cmp_le_i32_e32 vcc, 0, v2
	s_orn2_b64 s[18:19], vcc, exec
	s_branch .LBB0_1542

.LBB0_1556:
	s_or_b64 exec, exec, s[8:9]
	v_cvt_f32_u32_e32 v3, v0
	s_waitcnt vmcnt(0)
	v_readfirstlane_b32 s6, v2
	s_add_u32 s8, s40, 0x7500
	s_addc_u32 s9, s41, 0
	v_rcp_iflag_f32_e32 v3, v3
	v_add_u32_e32 v1, s6, v1
	v_add_u32_e32 v4, 1, v1
	s_mov_b64 s[10:11], 0
	v_mul_f32_e32 v2, 0x4f7ffffe, v3
	v_cvt_u32_f32_e32 v2, v2
	v_sub_u32_e32 v3, 0, v0
	v_mul_lo_u32 v3, v3, v2
	v_mul_hi_u32 v3, v2, v3
	v_add_u32_e32 v2, v2, v3
	v_mul_hi_u32 v2, v1, v2
	v_mul_lo_u32 v3, v2, v0
	v_sub_u32_e32 v1, v1, v3
	v_add_u32_e32 v5, 1, v2
	v_cmp_ge_u32_e32 vcc, v1, v0
	v_sub_u32_e32 v3, v1, v0
	s_nop 0
	v_cndmask_b32_e32 v2, v2, v5, vcc
	v_cndmask_b32_e32 v1, v1, v3, vcc
	v_add_u32_e32 v3, 1, v2
	v_cmp_ge_u32_e32 vcc, v1, v0
	s_nop 1
	v_cndmask_b32_e32 v2, v2, v3, vcc
	v_mul_lo_u32 v1, v0, v2
	v_add_u32_e32 v0, v1, v0
	v_cmp_ne_u32_e32 vcc, v4, v0
	v_mov_b32_e32 v5, v0
	v_mov_b64_e32 v[0:1], s[8:9]
	s_and_saveexec_b64 s[6:7], vcc
	s_cbranch_execz .LBB0_1568
	v_mov_b32_e32 v0, 0
	global_load_dword v1, v0, s[8:9] offset:-256 sc1
	s_mov_b64 s[14:15], 0
	s_waitcnt vmcnt(0)
	v_sub_u32_e32 v1, v1, v5
	v_cmp_gt_i32_e32 vcc, 0, v1
	s_and_saveexec_b64 s[12:13], vcc
	s_cbranch_execz .LBB0_1567
	s_add_u32 s10, s40, 0x4200
	s_addc_u32 s11, s41, 0
	s_mov_b32 s24, 1
	s_branch .LBB0_1560

.LBB0_1562:
	global_load_dword v1, v0, s[8:9] offset:-256 sc1
	s_add_i32 s24, s24, 1
	s_mov_b64 s[18:19], -1
	s_waitcnt vmcnt(0)
	v_sub_u32_e32 v1, v1, v5
	v_cmp_le_i32_e32 vcc, 0, v1
	s_orn2_b64 s[22:23], vcc, exec
	s_branch .LBB0_1559

.LBB0_1570:
	s_or_b64 exec, exec, s[6:7]
	s_mov_b64 s[6:7], exec
	v_mbcnt_lo_u32_b32 v0, s6, 0
	v_mbcnt_hi_u32_b32 v0, s7, v0
	v_cmp_eq_u32_e32 vcc, 0, v0
	s_and_saveexec_b64 s[8:9], vcc
	s_cbranch_execz .LBB0_1572
	s_bcnt1_i32_b64 s6, s[6:7]
	v_mov_b32_e32 v0, 0x2000
	v_mov_b32_e32 v1, s6
.LBB0_1572:
	s_or_b64 exec, exec, s[8:9]
	s_waitcnt vmcnt(0)
